# v38 + P2 compressed-attention token groups: per-wave balanced (i, 15-i, 16+i, 31-i) and waves 4-7 walk theirs in reverse order so SIMD partners are out of phase
# speedup vs baseline: 1.0073x; 1.0045x over previous
; __device__ __forceinline__ void cmp_task_lds(const Prm& P, Ctx& C, int b, int kvh, int tg, CStream& CS, const LAS bf16_t* wlb, const int NGW, bf16x8 (&qnx)[4], int& qnx_tg, const int tg_next) {
;     int lane; asm volatile("v_mbcnt_lo_u32_b32 %0, -1, 0\n\tv_mbcnt_hi_u32_b32 %0, -1, %0" : "=v"(lane));
;     const int q = lane & 31, hi = lane >> 5, slot = q >> 2, g = q & 3;
;     const int tok = 8 * tg + slot, head = 4 * kvh + g;
;     const size_t row = (size_t)b * SEQ + tok;
;     const int nvq = tok >= 31 ? ((tok - 31) >> 4) + 1 : 0;
;     const int tlast = 8 * tg + 7, nvmax = tlast >= 31 ? ((tlast - 31) >> 4) + 1 : 0, ntile = (nvmax + 31) >> 5;
;     const bf16_t* Qp = (const bf16_t*)(P.ws + WS_Q) + row * 512 + head * 64 + 8 * hi;
;     bf16x8 qf[4];
;     if (qnx_tg == tg) {
; #pragma unroll
;         for (int s = 0; s < 4; ++s) qf[s] = qnx[s];
;     } else {
; #pragma unroll
;         for (int s = 0; s < 4; ++s) qf[s] = *(const bf16x8*)(Qp + 16 * s);
; __device__ __forceinline__ void phase_cmp(const Prm& P, Ctx& C) {
;     ...
;         for (int i = C.wave; i * npw < 1024; i += NWAVES) {
;             const int tg = i * npw + ((i & 1) ? npw - 1 - j : j);
;             const int i2 = i + NWAVES; const int tgn = (i2 * npw < 1024) ? i2 * npw + ((i2 & 1) ? npw - 1 - j : j) : -1;
;             if (tg < 1024) cmp_task_lds(P, C, b, kvh, tg, CS, wlb, NGW, qnx, qnx_tg, (tgn >= 0 && tgn < 1024) ? tgn : -1);
.LBB0_1212:
	s_lshl_b32 s29, s96, 1
	s_add_i32 s29, s29, 24
	s_sub_i32 s29, s29, s76
	s_cmp_lt_u32 s96, 4
	s_cselect_b32 s28, s76, s29
	s_and_b32 s30, s28, 8
	s_lshr_b32 s30, s30, 3
	s_mul_i32 s30, s30, 7
	s_xor_b32 s28, s28, s30
	s_lshr_b32 s29, s77, 3
	s_sub_i32 s30, 31, s29
	s_bitcmp1_b32 s28, 0
	s_cselect_b32 s29, s30, s29
	s_lshl_b32 s28, s28, 5
	s_add_i32 s28, s28, s29
	s_sub_i32 s67, s28, s65
	s_add_i32 s76, s76, 8
	s_add_i32 s52, s65, s67
	s_mul_i32 s65, s76, s61
	s_lshl_b32 s29, s96, 1
	s_add_i32 s29, s29, 24
	s_sub_i32 s29, s29, s76
	s_cmp_lt_u32 s96, 4
	s_cselect_b32 s28, s76, s29
	s_and_b32 s30, s28, 8
	s_lshr_b32 s30, s30, 3
	s_mul_i32 s30, s30, 7
	s_xor_b32 s28, s28, s30
	s_lshr_b32 s29, s77, 3
	s_sub_i32 s30, 31, s29
	s_bitcmp1_b32 s28, 0
	s_cselect_b32 s29, s30, s29
	s_lshl_b32 s28, s28, 5
	s_add_i32 s28, s28, s29
	s_sub_i32 s67, s28, s65
	s_cmpk_lt_i32 s65, 0x400
	s_cselect_b64 s[0:1], -1, 0
	s_cmpk_gt_i32 s65, 0x3ff
	s_cselect_b64 s[50:51], -1, 0
	s_cmpk_gt_i32 s52, 0x3ff
	s_cbranch_scc1 .LBB0_1211
	v_mbcnt_lo_u32_b32 v219, -1, 0
	v_mbcnt_hi_u32_b32 v219, -1, v219
	s_lshl_b32 s8, s52, 3
	v_bfe_u32 v8, v219, 2, 3
	v_and_b32_e32 v221, 3, v219
	v_or_b32_e32 v6, s8, v8
	v_ashrrev_i32_e32 v220, 5, v219
	v_or_b32_e32 v9, s66, v221
	v_ashrrev_i32_e32 v7, 31, v6
	v_lshl_add_u64 v[194:195], s[36:37], 0, v[6:7]
	v_lshlrev_b32_e32 v1, 6, v9
	v_lshlrev_b32_e32 v18, 3, v220
	v_mov_b64_e32 v[150:151], v[134:135]
	v_mov_b64_e32 v[154:155], v[138:139]
	v_mov_b64_e32 v[158:159], v[142:143]
	v_mov_b64_e32 v[162:163], v[146:147]
	v_lshlrev_b64 v[196:197], 9, v[194:195]
	v_ashrrev_i32_e32 v19, 31, v18
	s_cmp_eq_u32 s75, s52
	v_lshlrev_b32_e32 v198, 1, v1
	v_mov_b64_e32 v[148:149], v[132:133]
	v_mov_b64_e32 v[152:153], v[136:137]
	v_mov_b64_e32 v[156:157], v[140:141]
	v_mov_b64_e32 v[160:161], v[144:145]
	s_cbranch_scc1 .LBB0_1215
	v_lshl_add_u64 v[2:3], v[196:197], 1, s[42:43]
	v_mov_b32_e32 v199, v0
	v_lshl_add_u64 v[2:3], v[2:3], 0, v[198:199]
	v_lshl_add_u64 v[2:3], v[18:19], 1, v[2:3]
	global_load_dwordx4 v[160:163], v[2:3], off offset:96
	global_load_dwordx4 v[156:159], v[2:3], off offset:64
	global_load_dwordx4 v[152:155], v[2:3], off offset:32
	global_load_dwordx4 v[148:151], v[2:3], off
